# S5 chunk phase: B/D MFMA chains read all LDS fragments up front (11 buffers), U quarter loads issued together
# speedup vs baseline: 1.0087x; 1.0087x over previous
; DI unsigned cvt_pk_bf16(float lo, float hi) { unsigned r; asm volatile("v_cvt_pk_bf16_f32 %0, %1, %2" : "=v"(r) : "v"(lo), "v"(hi)); return r; }
; DI float sigm(float x) { return __builtin_amdgcn_rcpf(1.f + __expf(-x)); }
; #define MFMA16(a, b, c) __builtin_amdgcn_mfma_f32_16x16x32_bf16((a), (b), (c), 0, 0, 0)
; DI void ssm_mfma_phase(PP P, int l, unsigned char* lds, int G, int cid) {
;     ...
; #pragma unroll
;             for (int rt = 0; rt < 2; ++rt)
; #pragma unroll
;                 for (int jt = 0; jt < 4; ++jt) {
;                     f32x4 acc = {0.f, 0.f, 0.f, 0.f};
; #pragma unroll
;                     for (int ks = 0; ks < 8; ++ks) { const bf16x8 bf = *(const bf16x8*)(UL + (jt * 16 + n16) * 264 + ks * 32 + q4 * 8); acc = MFMA16(akc[rt][ks], bf, acc); }
; #pragma unroll
;                     for (int ks = 0; ks < 4; ++ks) { const bf16x8 bf = *(const bf16x8*)(SL + (jt * 16 + n16) * 136 + ks * 32 + q4 * 8); acc = MFMA16(akc[rt][8 + ks], bf, acc); }
;                     float o[4];
; #pragma unroll
;                     for (int k = 0; k < 4; ++k) { const float y = acc[k]; o[k] = y * sigm(1.5957691216f * (y + 0.044715f * y * y * y)); }
;                     u32x2 w; w.x = cvt_pk_bf16(o[0], o[1]); w.y = cvt_pk_bf16(o[2], o[3]);
;                     const int t = qt * 1024 + (jt * 16 + n16) * 16 + (wave * 2 + rt);
;                     *(u32x2*)(YG + ((size_t)b * SEQ + t) * 1024 + g * 16 + 4 * q4) = w;
;                 }
.LBB0_247:
	s_waitcnt lgkmcnt(0)
	s_barrier
	s_nop 1
	ds_read_b128 v[156:159], v180
	ds_read_b128 v[182:185], v180 offset:64
	ds_read_b128 v[218:221], v180 offset:128
	ds_read_b128 v[222:225], v180 offset:192
	ds_read_b128 v[226:229], v180 offset:256
	ds_read_b128 v[230:233], v180 offset:320
	ds_read_b128 v[234:237], v180 offset:384
	ds_read_b128 v[238:241], v180 offset:448
	ds_read_b128 v[242:245], v179 offset:33792
	ds_read_b128 v[246:249], v179 offset:33856
	ds_read_b128 v[250:253], v179 offset:33920
	v_add_u32_e32 v160, s13, v174
	v_ashrrev_i32_e32 v161, 31, v160
	s_mov_b32 s4, 0x80000
	s_add_i32 s12, s12, 1
	s_cmp_eq_u32 s12, 4
	s_waitcnt lgkmcnt(10)
	v_mfma_f32_16x16x32_bf16 v[156:159], v[34:37], v[156:159], 0
	s_waitcnt lgkmcnt(9)
	v_mfma_f32_16x16x32_bf16 v[156:159], v[38:41], v[182:185], v[156:159]
	ds_read_b128 v[182:185], v179 offset:33984
	s_waitcnt lgkmcnt(9)
	v_mfma_f32_16x16x32_bf16 v[156:159], v[42:45], v[218:221], v[156:159]
	s_waitcnt lgkmcnt(8)
	v_mfma_f32_16x16x32_bf16 v[156:159], v[46:49], v[222:225], v[156:159]
	s_waitcnt lgkmcnt(7)
	v_mfma_f32_16x16x32_bf16 v[156:159], v[50:53], v[226:229], v[156:159]
	s_waitcnt lgkmcnt(6)
	v_mfma_f32_16x16x32_bf16 v[156:159], v[54:57], v[230:233], v[156:159]
	s_waitcnt lgkmcnt(5)
	v_mfma_f32_16x16x32_bf16 v[156:159], v[58:61], v[234:237], v[156:159]
	s_waitcnt lgkmcnt(4)
	v_mfma_f32_16x16x32_bf16 v[156:159], v[62:65], v[238:241], v[156:159]
	s_waitcnt lgkmcnt(3)
	v_mfma_f32_16x16x32_bf16 v[156:159], v[66:69], v[242:245], v[156:159]
	s_waitcnt lgkmcnt(2)
	v_mfma_f32_16x16x32_bf16 v[156:159], v[70:73], v[246:249], v[156:159]
	s_waitcnt lgkmcnt(1)
	v_mfma_f32_16x16x32_bf16 v[156:159], v[74:77], v[250:253], v[156:159]
	s_waitcnt lgkmcnt(0)
	v_mfma_f32_16x16x32_bf16 v[156:159], v[78:81], v[182:185], v[156:159]
	s_nop 7
	v_mul_f32_e32 v143, 0x3d372713, v156
	v_mul_f32_e32 v143, v156, v143
	v_fma_f32 v143, v156, v143, v156
	v_mul_f32_e32 v143, 0x3fcc422a, v143
	v_mul_f32_e32 v143, 0xbfb8aa3b, v143
	v_exp_f32_e32 v143, v143
	s_nop 0
	v_add_f32_e32 v143, 1.0, v143
	v_rcp_f32_e32 v143, v143
	s_nop 0
	v_mul_f32_e32 v143, v156, v143
	v_mul_f32_e32 v156, 0x3d372713, v157
	v_mul_f32_e32 v156, v157, v156
	v_fma_f32 v156, v157, v156, v157
	v_mul_f32_e32 v156, 0x3fcc422a, v156
	v_mul_f32_e32 v156, 0xbfb8aa3b, v156
	v_exp_f32_e32 v156, v156
	s_nop 0
	v_add_f32_e32 v156, 1.0, v156
	v_rcp_f32_e32 v156, v156
	s_nop 0
	v_mul_f32_e32 v156, v157, v156
	v_mul_f32_e32 v157, 0x3d372713, v158
	v_mul_f32_e32 v157, v158, v157
	v_fma_f32 v157, v158, v157, v158
	v_mul_f32_e32 v157, 0x3fcc422a, v157
	v_mul_f32_e32 v157, 0xbfb8aa3b, v157
	v_exp_f32_e32 v157, v157
	v_cvt_pk_bf16_f32 v156, v143, v156
	s_nop 0
	v_add_f32_e32 v157, 1.0, v157
	v_rcp_f32_e32 v157, v157
	s_nop 0
	v_mul_f32_e32 v157, v158, v157
	v_mul_f32_e32 v158, 0x3d372713, v159
	v_mul_f32_e32 v158, v159, v158
	v_fma_f32 v158, v159, v158, v159
	v_mul_f32_e32 v158, 0x3fcc422a, v158
	v_mul_f32_e32 v158, 0xbfb8aa3b, v158
	v_exp_f32_e32 v158, v158
	s_nop 0
	v_add_f32_e32 v158, 1.0, v158
	v_rcp_f32_e32 v158, v158
	s_nop 0
	v_mul_f32_e32 v158, v159, v158
	v_cvt_pk_bf16_f32 v157, v157, v158
	v_lshlrev_b64 v[158:159], 11, v[160:161]
	v_lshl_add_u64 v[170:171], v[146:147], 0, v[158:159]
	global_store_dwordx2 v[170:171], v[156:157], off
	ds_read_b128 v[156:159], v180 offset:8448
	ds_read_b128 v[182:185], v180 offset:8512
	ds_read_b128 v[218:221], v180 offset:8576
	ds_read_b128 v[222:225], v180 offset:8640
	ds_read_b128 v[226:229], v180 offset:8704
	ds_read_b128 v[230:233], v180 offset:8768
	ds_read_b128 v[234:237], v180 offset:8832
	ds_read_b128 v[238:241], v180 offset:8896
	ds_read_b128 v[242:245], v179 offset:38144
	ds_read_b128 v[246:249], v179 offset:38208
	ds_read_b128 v[250:253], v179 offset:38272
	v_or_b32_e32 v160, 1, v160
	s_waitcnt lgkmcnt(10)
	v_mfma_f32_16x16x32_bf16 v[156:159], v[34:37], v[156:159], 0
	s_waitcnt lgkmcnt(9)
	v_mfma_f32_16x16x32_bf16 v[156:159], v[38:41], v[182:185], v[156:159]
	ds_read_b128 v[182:185], v179 offset:38336
	s_waitcnt lgkmcnt(9)
	v_mfma_f32_16x16x32_bf16 v[156:159], v[42:45], v[218:221], v[156:159]
	s_waitcnt lgkmcnt(8)
	v_mfma_f32_16x16x32_bf16 v[156:159], v[46:49], v[222:225], v[156:159]
	s_waitcnt lgkmcnt(7)
	v_mfma_f32_16x16x32_bf16 v[156:159], v[50:53], v[226:229], v[156:159]
	s_waitcnt lgkmcnt(6)
	v_mfma_f32_16x16x32_bf16 v[156:159], v[54:57], v[230:233], v[156:159]
	s_waitcnt lgkmcnt(5)
	v_mfma_f32_16x16x32_bf16 v[156:159], v[58:61], v[234:237], v[156:159]
	s_waitcnt lgkmcnt(4)
	v_mfma_f32_16x16x32_bf16 v[156:159], v[62:65], v[238:241], v[156:159]
	s_waitcnt lgkmcnt(3)
	v_mfma_f32_16x16x32_bf16 v[156:159], v[66:69], v[242:245], v[156:159]
	s_waitcnt lgkmcnt(2)
	v_mfma_f32_16x16x32_bf16 v[156:159], v[70:73], v[246:249], v[156:159]
	s_waitcnt lgkmcnt(1)
	v_mfma_f32_16x16x32_bf16 v[156:159], v[74:77], v[250:253], v[156:159]
	s_waitcnt lgkmcnt(0)
; DI unsigned cvt_pk_bf16(float lo, float hi) { unsigned r; asm volatile("v_cvt_pk_bf16_f32 %0, %1, %2" : "=v"(r) : "v"(lo), "v"(hi)); return r; }
; DI float sigm(float x) { return __builtin_amdgcn_rcpf(1.f + __expf(-x)); }
; #define MFMA16(a, b, c) __builtin_amdgcn_mfma_f32_16x16x32_bf16((a), (b), (c), 0, 0, 0)
; DI void ssm_mfma_phase(PP P, int l, unsigned char* lds, int G, int cid) {
;     ...
; #pragma unroll
;             for (int rt = 0; rt < 2; ++rt)
; #pragma unroll
;                 for (int jt = 0; jt < 4; ++jt) {
;                     f32x4 acc = {0.f, 0.f, 0.f, 0.f};
; #pragma unroll
;                     for (int ks = 0; ks < 8; ++ks) { const bf16x8 bf = *(const bf16x8*)(UL + (jt * 16 + n16) * 264 + ks * 32 + q4 * 8); acc = MFMA16(akc[rt][ks], bf, acc); }
; #pragma unroll
;                     for (int ks = 0; ks < 4; ++ks) { const bf16x8 bf = *(const bf16x8*)(SL + (jt * 16 + n16) * 136 + ks * 32 + q4 * 8); acc = MFMA16(akc[rt][8 + ks], bf, acc); }
;                     float o[4];
; #pragma unroll
;                     for (int k = 0; k < 4; ++k) { const float y = acc[k]; o[k] = y * sigm(1.5957691216f * (y + 0.044715f * y * y * y)); }
;                     u32x2 w; w.x = cvt_pk_bf16(o[0], o[1]); w.y = cvt_pk_bf16(o[2], o[3]);
;                     const int t = qt * 1024 + (jt * 16 + n16) * 16 + (wave * 2 + rt);
;                     *(u32x2*)(YG + ((size_t)b * SEQ + t) * 1024 + g * 16 + 4 * q4) = w;
;                 }
	v_mfma_f32_16x16x32_bf16 v[156:159], v[78:81], v[182:185], v[156:159]
	s_nop 7
	v_mul_f32_e32 v143, 0x3d372713, v156
	v_mul_f32_e32 v143, v156, v143
	v_fma_f32 v143, v156, v143, v156
	v_mul_f32_e32 v143, 0x3fcc422a, v143
	v_mul_f32_e32 v143, 0xbfb8aa3b, v143
	v_exp_f32_e32 v143, v143
	s_nop 0
	v_add_f32_e32 v143, 1.0, v143
	v_rcp_f32_e32 v143, v143
	s_nop 0
	v_mul_f32_e32 v143, v156, v143
	v_mul_f32_e32 v156, 0x3d372713, v157
	v_mul_f32_e32 v156, v157, v156
	v_fma_f32 v156, v157, v156, v157
	v_mul_f32_e32 v156, 0x3fcc422a, v156
	v_mul_f32_e32 v156, 0xbfb8aa3b, v156
	v_exp_f32_e32 v156, v156
	s_nop 0
	v_add_f32_e32 v156, 1.0, v156
	v_rcp_f32_e32 v156, v156
	s_nop 0
	v_mul_f32_e32 v156, v157, v156
	v_mul_f32_e32 v157, 0x3d372713, v158
	v_mul_f32_e32 v157, v158, v157
	v_fma_f32 v157, v158, v157, v158
	v_mul_f32_e32 v157, 0x3fcc422a, v157
	v_mul_f32_e32 v157, 0xbfb8aa3b, v157
	v_exp_f32_e32 v157, v157
	s_nop 0
	v_add_f32_e32 v157, 1.0, v157
	v_rcp_f32_e32 v157, v157
	s_nop 0
	v_mul_f32_e32 v157, v158, v157
	v_mul_f32_e32 v158, 0x3d372713, v159
	v_mul_f32_e32 v158, v159, v158
	v_fma_f32 v158, v159, v158, v159
	v_mul_f32_e32 v158, 0x3fcc422a, v158
	v_mul_f32_e32 v158, 0xbfb8aa3b, v158
	v_exp_f32_e32 v158, v158
	s_nop 0
	v_add_f32_e32 v158, 1.0, v158
	v_rcp_f32_e32 v158, v158
	s_nop 0
	v_mul_f32_e32 v159, v159, v158
	v_cvt_pk_bf16_f32 v158, v143, v156
	v_cvt_pk_bf16_f32 v159, v157, v159
	ds_read_b128 v[182:185], v180 offset:16896
	ds_read_b128 v[186:189], v180 offset:16960
	ds_read_b128 v[218:221], v180 offset:17024
	ds_read_b128 v[222:225], v180 offset:17088
	ds_read_b128 v[226:229], v180 offset:17152
	ds_read_b128 v[230:233], v180 offset:17216
	ds_read_b128 v[234:237], v180 offset:17280
	ds_read_b128 v[238:241], v180 offset:17344
	ds_read_b128 v[242:245], v179 offset:42496
	ds_read_b128 v[246:249], v179 offset:42560
	ds_read_b128 v[250:253], v179 offset:42624
	v_add_co_u32_e32 v156, vcc, s4, v170
	s_mov_b32 s4, 0x100000
	v_addc_co_u32_e32 v157, vcc, 0, v171, vcc
	global_store_dwordx2 v[156:157], v[158:159], off
	s_waitcnt lgkmcnt(10)
	v_mfma_f32_16x16x32_bf16 v[182:185], v[34:37], v[182:185], 0
	s_waitcnt lgkmcnt(9)
	v_mfma_f32_16x16x32_bf16 v[182:185], v[38:41], v[186:189], v[182:185]
	ds_read_b128 v[186:189], v179 offset:42688
	s_waitcnt lgkmcnt(9)
	v_mfma_f32_16x16x32_bf16 v[182:185], v[42:45], v[218:221], v[182:185]
	s_waitcnt lgkmcnt(8)
	v_mfma_f32_16x16x32_bf16 v[182:185], v[46:49], v[222:225], v[182:185]
	s_waitcnt lgkmcnt(7)
	v_mfma_f32_16x16x32_bf16 v[182:185], v[50:53], v[226:229], v[182:185]
	s_waitcnt lgkmcnt(6)
	v_mfma_f32_16x16x32_bf16 v[182:185], v[54:57], v[230:233], v[182:185]
	s_waitcnt lgkmcnt(5)
	v_mfma_f32_16x16x32_bf16 v[182:185], v[58:61], v[234:237], v[182:185]
	s_waitcnt lgkmcnt(4)
	v_mfma_f32_16x16x32_bf16 v[182:185], v[62:65], v[238:241], v[182:185]
	s_waitcnt lgkmcnt(3)
	v_mfma_f32_16x16x32_bf16 v[182:185], v[66:69], v[242:245], v[182:185]
	s_waitcnt lgkmcnt(2)
	v_mfma_f32_16x16x32_bf16 v[182:185], v[70:73], v[246:249], v[182:185]
	s_waitcnt lgkmcnt(1)
	v_mfma_f32_16x16x32_bf16 v[182:185], v[74:77], v[250:253], v[182:185]
	s_waitcnt lgkmcnt(0)
	v_mfma_f32_16x16x32_bf16 v[182:185], v[78:81], v[186:189], v[182:185]
	s_nop 7
	v_mul_f32_e32 v143, 0x3d372713, v182
	v_mul_f32_e32 v158, 0x3d372713, v183
	v_mul_f32_e32 v159, 0x3d372713, v184
	v_mul_f32_e32 v161, 0x3d372713, v185
	v_mul_f32_e32 v143, v182, v143
	v_mul_f32_e32 v158, v183, v158
	v_mul_f32_e32 v159, v184, v159
	v_mul_f32_e32 v161, v185, v161
	v_fma_f32 v143, v182, v143, v182
	v_fma_f32 v158, v183, v158, v183
	v_fma_f32 v159, v184, v159, v184
	v_fma_f32 v161, v185, v161, v185
	v_mul_f32_e32 v143, 0x3fcc422a, v143
	v_mul_f32_e32 v158, 0x3fcc422a, v158
	v_mul_f32_e32 v159, 0x3fcc422a, v159
	v_mul_f32_e32 v161, 0x3fcc422a, v161
	v_mul_f32_e32 v143, 0xbfb8aa3b, v143
	v_mul_f32_e32 v158, 0xbfb8aa3b, v158
	v_mul_f32_e32 v159, 0xbfb8aa3b, v159
	v_mul_f32_e32 v161, 0xbfb8aa3b, v161
	v_exp_f32_e32 v143, v143
	v_exp_f32_e32 v158, v158
	v_exp_f32_e32 v159, v159
	v_exp_f32_e32 v161, v161
	v_add_f32_e32 v143, 1.0, v143
	v_add_f32_e32 v158, 1.0, v158
	v_add_f32_e32 v159, 1.0, v159
	v_add_f32_e32 v161, 1.0, v161
	v_rcp_f32_e32 v143, v143
	v_rcp_f32_e32 v158, v158
	v_rcp_f32_e32 v159, v159
	v_rcp_f32_e32 v161, v161
	v_mul_f32_e32 v143, v182, v143
	v_mul_f32_e32 v158, v183, v158
	v_mul_f32_e32 v159, v184, v159
	v_mul_f32_e32 v161, v185, v161
	v_cvt_pk_bf16_f32 v168, v143, v158
	v_cvt_pk_bf16_f32 v169, v159, v161
	ds_read_b128 v[182:185], v180 offset:25344
	ds_read_b128 v[186:189], v180 offset:25408
	ds_read_b128 v[218:221], v180 offset:25472
	ds_read_b128 v[222:225], v180 offset:25536
	ds_read_b128 v[226:229], v180 offset:25600
	ds_read_b128 v[230:233], v180 offset:25664
	ds_read_b128 v[234:237], v180 offset:25728
	ds_read_b128 v[238:241], v180 offset:25792
	ds_read_b128 v[242:245], v179 offset:46848
	ds_read_b128 v[246:249], v179 offset:46912
	ds_read_b128 v[250:253], v179 offset:46976
	v_add_co_u32_e32 v158, vcc, s4, v170
	s_mov_b32 s4, 0x180000
	v_addc_co_u32_e32 v159, vcc, 0, v171, vcc
	global_store_dwordx2 v[158:159], v[168:169], off
	v_add_co_u32_e32 v170, vcc, s4, v170
	v_addc_co_u32_e32 v171, vcc, 0, v171, vcc
	s_waitcnt lgkmcnt(10)
	v_mfma_f32_16x16x32_bf16 v[182:185], v[34:37], v[182:185], 0
	s_waitcnt lgkmcnt(9)
	v_mfma_f32_16x16x32_bf16 v[182:185], v[38:41], v[186:189], v[182:185]
	ds_read_b128 v[186:189], v179 offset:47040
	s_waitcnt lgkmcnt(9)
	v_mfma_f32_16x16x32_bf16 v[182:185], v[42:45], v[218:221], v[182:185]
	s_waitcnt lgkmcnt(8)
	v_mfma_f32_16x16x32_bf16 v[182:185], v[46:49], v[222:225], v[182:185]
	s_waitcnt lgkmcnt(7)
; DI unsigned cvt_pk_bf16(float lo, float hi) { unsigned r; asm volatile("v_cvt_pk_bf16_f32 %0, %1, %2" : "=v"(r) : "v"(lo), "v"(hi)); return r; }
; DI float sigm(float x) { return __builtin_amdgcn_rcpf(1.f + __expf(-x)); }
; #define MFMA16(a, b, c) __builtin_amdgcn_mfma_f32_16x16x32_bf16((a), (b), (c), 0, 0, 0)
; DI void ssm_mfma_phase(PP P, int l, unsigned char* lds, int G, int cid) {
;     ...
; #pragma unroll
;             for (int rt = 0; rt < 2; ++rt)
; #pragma unroll
;                 for (int jt = 0; jt < 4; ++jt) {
;                     f32x4 acc = {0.f, 0.f, 0.f, 0.f};
; #pragma unroll
;                     for (int ks = 0; ks < 8; ++ks) { const bf16x8 bf = *(const bf16x8*)(UL + (jt * 16 + n16) * 264 + ks * 32 + q4 * 8); acc = MFMA16(akc[rt][ks], bf, acc); }
; #pragma unroll
;                     for (int ks = 0; ks < 4; ++ks) { const bf16x8 bf = *(const bf16x8*)(SL + (jt * 16 + n16) * 136 + ks * 32 + q4 * 8); acc = MFMA16(akc[rt][8 + ks], bf, acc); }
;                     float o[4];
; #pragma unroll
;                     for (int k = 0; k < 4; ++k) { const float y = acc[k]; o[k] = y * sigm(1.5957691216f * (y + 0.044715f * y * y * y)); }
;                     u32x2 w; w.x = cvt_pk_bf16(o[0], o[1]); w.y = cvt_pk_bf16(o[2], o[3]);
;                     const int t = qt * 1024 + (jt * 16 + n16) * 16 + (wave * 2 + rt);
;                     *(u32x2*)(YG + ((size_t)b * SEQ + t) * 1024 + g * 16 + 4 * q4) = w;
;                 }
	v_mfma_f32_16x16x32_bf16 v[182:185], v[50:53], v[226:229], v[182:185]
	s_waitcnt lgkmcnt(6)
	v_mfma_f32_16x16x32_bf16 v[182:185], v[54:57], v[230:233], v[182:185]
	s_waitcnt lgkmcnt(5)
	v_mfma_f32_16x16x32_bf16 v[182:185], v[58:61], v[234:237], v[182:185]
	s_waitcnt lgkmcnt(4)
	v_mfma_f32_16x16x32_bf16 v[182:185], v[62:65], v[238:241], v[182:185]
	s_waitcnt lgkmcnt(3)
	v_mfma_f32_16x16x32_bf16 v[182:185], v[66:69], v[242:245], v[182:185]
	s_waitcnt lgkmcnt(2)
	v_mfma_f32_16x16x32_bf16 v[182:185], v[70:73], v[246:249], v[182:185]
	s_waitcnt lgkmcnt(1)
	v_mfma_f32_16x16x32_bf16 v[182:185], v[74:77], v[250:253], v[182:185]
	s_waitcnt lgkmcnt(0)
	v_mfma_f32_16x16x32_bf16 v[182:185], v[78:81], v[186:189], v[182:185]
	s_nop 7
	v_mul_f32_e32 v168, 0x3d372713, v185
	v_mul_f32_e32 v143, 0x3d372713, v182
	v_mul_f32_e32 v161, 0x3d372713, v183
	v_mul_f32_e32 v162, 0x3d372713, v184
	v_mul_f32_e32 v168, v185, v168
	v_mul_f32_e32 v143, v182, v143
	v_mul_f32_e32 v161, v183, v161
	v_mul_f32_e32 v162, v184, v162
	v_fma_f32 v168, v185, v168, v185
	v_fma_f32 v143, v182, v143, v182
	v_fma_f32 v161, v183, v161, v183
	v_fma_f32 v162, v184, v162, v184
	v_mul_f32_e32 v168, 0x3fcc422a, v168
	v_mul_f32_e32 v143, 0x3fcc422a, v143
	v_mul_f32_e32 v161, 0x3fcc422a, v161
	v_mul_f32_e32 v162, 0x3fcc422a, v162
	v_mul_f32_e32 v168, 0xbfb8aa3b, v168
	v_mul_f32_e32 v143, 0xbfb8aa3b, v143
	v_mul_f32_e32 v161, 0xbfb8aa3b, v161
	v_mul_f32_e32 v162, 0xbfb8aa3b, v162
	v_exp_f32_e32 v168, v168
	v_exp_f32_e32 v143, v143
	v_exp_f32_e32 v161, v161
	v_exp_f32_e32 v162, v162
	v_add_f32_e32 v168, 1.0, v168
	v_add_f32_e32 v143, 1.0, v143
	v_add_f32_e32 v161, 1.0, v161
	v_add_f32_e32 v162, 1.0, v162
	v_rcp_f32_e32 v168, v168
	v_rcp_f32_e32 v143, v143
	v_rcp_f32_e32 v161, v161
	v_rcp_f32_e32 v162, v162
	v_mul_f32_e32 v169, v185, v168
	v_mul_f32_e32 v143, v182, v143
	v_mul_f32_e32 v161, v183, v161
	v_mul_f32_e32 v162, v184, v162
	v_cvt_pk_bf16_f32 v168, v143, v161
	v_cvt_pk_bf16_f32 v169, v162, v169
	ds_read_b128 v[182:185], v180
	ds_read_b128 v[186:189], v180 offset:64
	ds_read_b128 v[218:221], v180 offset:128
	ds_read_b128 v[222:225], v180 offset:192
	ds_read_b128 v[226:229], v180 offset:256
	ds_read_b128 v[230:233], v180 offset:320
	ds_read_b128 v[234:237], v180 offset:384
	ds_read_b128 v[238:241], v180 offset:448
	ds_read_b128 v[242:245], v179 offset:33792
	ds_read_b128 v[246:249], v179 offset:33856
	ds_read_b128 v[250:253], v179 offset:33920
	global_store_dwordx2 v[170:171], v[168:169], off
	s_waitcnt lgkmcnt(10)
	v_mfma_f32_16x16x32_bf16 v[182:185], v[82:85], v[182:185], 0
	s_waitcnt lgkmcnt(9)
	v_mfma_f32_16x16x32_bf16 v[182:185], v[86:89], v[186:189], v[182:185]
	ds_read_b128 v[186:189], v179 offset:33984
	s_waitcnt lgkmcnt(9)
	v_mfma_f32_16x16x32_bf16 v[182:185], v[90:93], v[218:221], v[182:185]
	s_waitcnt lgkmcnt(8)
	v_mfma_f32_16x16x32_bf16 v[182:185], v[94:97], v[222:225], v[182:185]
	s_waitcnt lgkmcnt(7)
	v_mfma_f32_16x16x32_bf16 v[182:185], v[98:101], v[226:229], v[182:185]
	s_waitcnt lgkmcnt(6)
	v_mfma_f32_16x16x32_bf16 v[182:185], v[102:105], v[230:233], v[182:185]
	s_waitcnt lgkmcnt(5)
	v_mfma_f32_16x16x32_bf16 v[182:185], v[106:109], v[234:237], v[182:185]
	s_waitcnt lgkmcnt(4)
	v_mfma_f32_16x16x32_bf16 v[182:185], v[110:113], v[238:241], v[182:185]
	s_waitcnt lgkmcnt(3)
	v_mfma_f32_16x16x32_bf16 v[182:185], v[114:117], v[242:245], v[182:185]
	s_waitcnt lgkmcnt(2)
	v_mfma_f32_16x16x32_bf16 v[182:185], v[118:121], v[246:249], v[182:185]
	s_waitcnt lgkmcnt(1)
	v_mfma_f32_16x16x32_bf16 v[182:185], v[122:125], v[250:253], v[182:185]
	s_waitcnt lgkmcnt(0)
	v_mfma_f32_16x16x32_bf16 v[182:185], v[126:129], v[186:189], v[182:185]
	s_nop 7
	v_mul_f32_e32 v168, 0x3d372713, v185
	v_mul_f32_e32 v143, 0x3d372713, v182
	v_mul_f32_e32 v161, 0x3d372713, v183
	v_mul_f32_e32 v162, 0x3d372713, v184
	v_mul_f32_e32 v168, v185, v168
	v_mul_f32_e32 v143, v182, v143
	v_mul_f32_e32 v161, v183, v161
	v_mul_f32_e32 v162, v184, v162
	v_fma_f32 v168, v185, v168, v185
	v_fma_f32 v143, v182, v143, v182
	v_fma_f32 v161, v183, v161, v183
	v_fma_f32 v162, v184, v162, v184
	v_mul_f32_e32 v168, 0x3fcc422a, v168
	v_mul_f32_e32 v143, 0x3fcc422a, v143
	v_mul_f32_e32 v161, 0x3fcc422a, v161
	v_mul_f32_e32 v162, 0x3fcc422a, v162
	v_mul_f32_e32 v168, 0xbfb8aa3b, v168
	v_mul_f32_e32 v143, 0xbfb8aa3b, v143
	v_mul_f32_e32 v161, 0xbfb8aa3b, v161
	v_mul_f32_e32 v162, 0xbfb8aa3b, v162
	v_exp_f32_e32 v168, v168
	v_exp_f32_e32 v143, v143
	v_exp_f32_e32 v161, v161
	v_exp_f32_e32 v162, v162
	v_add_f32_e32 v168, 1.0, v168
	v_add_f32_e32 v143, 1.0, v143
	v_add_f32_e32 v161, 1.0, v161
	v_add_f32_e32 v162, 1.0, v162
	v_rcp_f32_e32 v168, v168
	v_rcp_f32_e32 v143, v143
	v_rcp_f32_e32 v161, v161
	v_rcp_f32_e32 v162, v162
	v_mul_f32_e32 v169, v185, v168
	v_mul_f32_e32 v143, v182, v143
	v_mul_f32_e32 v161, v183, v161
	v_mul_f32_e32 v162, v184, v162
	v_cvt_pk_bf16_f32 v168, v143, v161
	v_cvt_pk_bf16_f32 v169, v162, v169
	ds_read_b128 v[182:185], v180 offset:8448
	ds_read_b128 v[186:189], v180 offset:8512
	ds_read_b128 v[218:221], v180 offset:8576
	ds_read_b128 v[222:225], v180 offset:8640
	ds_read_b128 v[226:229], v180 offset:8704
	ds_read_b128 v[230:233], v180 offset:8768
	ds_read_b128 v[234:237], v180 offset:8832
	ds_read_b128 v[238:241], v180 offset:8896
	ds_read_b128 v[242:245], v179 offset:38144
	ds_read_b128 v[246:249], v179 offset:38208
	ds_read_b128 v[250:253], v179 offset:38272
	v_ashrrev_i32_e32 v161, 31, v160
	v_lshlrev_b64 v[160:161], 11, v[160:161]
	v_lshl_add_u64 v[160:161], v[146:147], 0, v[160:161]
	global_store_dwordx2 v[160:161], v[168:169], off
	s_waitcnt lgkmcnt(10)
	v_mfma_f32_16x16x32_bf16 v[182:185], v[82:85], v[182:185], 0
	s_waitcnt lgkmcnt(9)
; DI unsigned cvt_pk_bf16(float lo, float hi) { unsigned r; asm volatile("v_cvt_pk_bf16_f32 %0, %1, %2" : "=v"(r) : "v"(lo), "v"(hi)); return r; }
; DI float sigm(float x) { return __builtin_amdgcn_rcpf(1.f + __expf(-x)); }
; #define MFMA16(a, b, c) __builtin_amdgcn_mfma_f32_16x16x32_bf16((a), (b), (c), 0, 0, 0)
; DI void ssm_mfma_phase(PP P, int l, unsigned char* lds, int G, int cid) {
;     ...
; #pragma unroll
;             for (int rt = 0; rt < 2; ++rt)
; #pragma unroll
;                 for (int jt = 0; jt < 4; ++jt) {
;                     f32x4 acc = {0.f, 0.f, 0.f, 0.f};
; #pragma unroll
;                     for (int ks = 0; ks < 8; ++ks) { const bf16x8 bf = *(const bf16x8*)(UL + (jt * 16 + n16) * 264 + ks * 32 + q4 * 8); acc = MFMA16(akc[rt][ks], bf, acc); }
; #pragma unroll
;                     for (int ks = 0; ks < 4; ++ks) { const bf16x8 bf = *(const bf16x8*)(SL + (jt * 16 + n16) * 136 + ks * 32 + q4 * 8); acc = MFMA16(akc[rt][8 + ks], bf, acc); }
;                     float o[4];
; #pragma unroll
;                     for (int k = 0; k < 4; ++k) { const float y = acc[k]; o[k] = y * sigm(1.5957691216f * (y + 0.044715f * y * y * y)); }
;                     u32x2 w; w.x = cvt_pk_bf16(o[0], o[1]); w.y = cvt_pk_bf16(o[2], o[3]);
;                     const int t = qt * 1024 + (jt * 16 + n16) * 16 + (wave * 2 + rt);
;                     *(u32x2*)(YG + ((size_t)b * SEQ + t) * 1024 + g * 16 + 4 * q4) = w;
;                 }
	v_mfma_f32_16x16x32_bf16 v[182:185], v[86:89], v[186:189], v[182:185]
	ds_read_b128 v[186:189], v179 offset:38336
	s_waitcnt lgkmcnt(9)
	v_mfma_f32_16x16x32_bf16 v[182:185], v[90:93], v[218:221], v[182:185]
	s_waitcnt lgkmcnt(8)
	v_mfma_f32_16x16x32_bf16 v[182:185], v[94:97], v[222:225], v[182:185]
	s_waitcnt lgkmcnt(7)
	v_mfma_f32_16x16x32_bf16 v[182:185], v[98:101], v[226:229], v[182:185]
	s_waitcnt lgkmcnt(6)
	v_mfma_f32_16x16x32_bf16 v[182:185], v[102:105], v[230:233], v[182:185]
	s_waitcnt lgkmcnt(5)
	v_mfma_f32_16x16x32_bf16 v[182:185], v[106:109], v[234:237], v[182:185]
	s_waitcnt lgkmcnt(4)
	v_mfma_f32_16x16x32_bf16 v[182:185], v[110:113], v[238:241], v[182:185]
	s_waitcnt lgkmcnt(3)
	v_mfma_f32_16x16x32_bf16 v[182:185], v[114:117], v[242:245], v[182:185]
	s_waitcnt lgkmcnt(2)
	v_mfma_f32_16x16x32_bf16 v[182:185], v[118:121], v[246:249], v[182:185]
	s_waitcnt lgkmcnt(1)
	v_mfma_f32_16x16x32_bf16 v[182:185], v[122:125], v[250:253], v[182:185]
	s_waitcnt lgkmcnt(0)
	v_mfma_f32_16x16x32_bf16 v[182:185], v[126:129], v[186:189], v[182:185]
	s_nop 7
	v_mul_f32_e32 v160, 0x3d372713, v183
	v_mul_f32_e32 v161, 0x3d372713, v184
	v_mul_f32_e32 v143, 0x3d372713, v182
	v_mul_f32_e32 v160, v183, v160
	v_mul_f32_e32 v161, v184, v161
	v_mul_f32_e32 v162, 0x3d372713, v185
	v_mul_f32_e32 v143, v182, v143
	v_fma_f32 v160, v183, v160, v183
	v_fma_f32 v161, v184, v161, v184
	v_mul_f32_e32 v162, v185, v162
	v_fma_f32 v143, v182, v143, v182
	v_mul_f32_e32 v160, 0x3fcc422a, v160
	v_mul_f32_e32 v161, 0x3fcc422a, v161
	v_fma_f32 v162, v185, v162, v185
	v_mul_f32_e32 v143, 0x3fcc422a, v143
	v_mul_f32_e32 v160, 0xbfb8aa3b, v160
	v_mul_f32_e32 v161, 0xbfb8aa3b, v161
	v_mul_f32_e32 v162, 0x3fcc422a, v162
	v_mul_f32_e32 v143, 0xbfb8aa3b, v143
	v_exp_f32_e32 v160, v160
	v_exp_f32_e32 v161, v161
	v_mul_f32_e32 v162, 0xbfb8aa3b, v162
	v_exp_f32_e32 v143, v143
	v_exp_f32_e32 v162, v162
	v_add_f32_e32 v160, 1.0, v160
	v_add_f32_e32 v161, 1.0, v161
	v_add_f32_e32 v143, 1.0, v143
	v_rcp_f32_e32 v160, v160
	v_rcp_f32_e32 v161, v161
	v_add_f32_e32 v162, 1.0, v162
	v_rcp_f32_e32 v143, v143
	v_rcp_f32_e32 v162, v162
	v_mul_f32_e32 v160, v183, v160
	v_mul_f32_e32 v161, v184, v161
	v_mul_f32_e32 v143, v182, v143
	v_mul_f32_e32 v162, v185, v162
	v_cvt_pk_bf16_f32 v160, v143, v160
	v_cvt_pk_bf16_f32 v161, v161, v162
	ds_read_b128 v[182:185], v180 offset:16896
	ds_read_b128 v[186:189], v180 offset:16960
	ds_read_b128 v[218:221], v180 offset:17024
	ds_read_b128 v[222:225], v180 offset:17088
	ds_read_b128 v[226:229], v180 offset:17152
	ds_read_b128 v[230:233], v180 offset:17216
	ds_read_b128 v[234:237], v180 offset:17280
	ds_read_b128 v[238:241], v180 offset:17344
	ds_read_b128 v[242:245], v179 offset:42496
	ds_read_b128 v[246:249], v179 offset:42560
	ds_read_b128 v[250:253], v179 offset:42624
	global_store_dwordx2 v[156:157], v[160:161], off offset:2048
	s_waitcnt lgkmcnt(10)
	v_mfma_f32_16x16x32_bf16 v[182:185], v[82:85], v[182:185], 0
	s_waitcnt lgkmcnt(9)
	v_mfma_f32_16x16x32_bf16 v[182:185], v[86:89], v[186:189], v[182:185]
	ds_read_b128 v[186:189], v179 offset:42688
	s_waitcnt lgkmcnt(9)
	v_mfma_f32_16x16x32_bf16 v[182:185], v[90:93], v[218:221], v[182:185]
	s_waitcnt lgkmcnt(8)
	v_mfma_f32_16x16x32_bf16 v[182:185], v[94:97], v[222:225], v[182:185]
	s_waitcnt lgkmcnt(7)
	v_mfma_f32_16x16x32_bf16 v[182:185], v[98:101], v[226:229], v[182:185]
	s_waitcnt lgkmcnt(6)
	v_mfma_f32_16x16x32_bf16 v[182:185], v[102:105], v[230:233], v[182:185]
	s_waitcnt lgkmcnt(5)
	v_mfma_f32_16x16x32_bf16 v[182:185], v[106:109], v[234:237], v[182:185]
	s_waitcnt lgkmcnt(4)
	v_mfma_f32_16x16x32_bf16 v[182:185], v[110:113], v[238:241], v[182:185]
	s_waitcnt lgkmcnt(3)
	v_mfma_f32_16x16x32_bf16 v[182:185], v[114:117], v[242:245], v[182:185]
	s_waitcnt lgkmcnt(2)
	v_mfma_f32_16x16x32_bf16 v[182:185], v[118:121], v[246:249], v[182:185]
	s_waitcnt lgkmcnt(1)
	v_mfma_f32_16x16x32_bf16 v[182:185], v[122:125], v[250:253], v[182:185]
	s_waitcnt lgkmcnt(0)
	v_mfma_f32_16x16x32_bf16 v[182:185], v[126:129], v[186:189], v[182:185]
	s_nop 7
	v_mul_f32_e32 v156, 0x3d372713, v183
	v_mul_f32_e32 v157, 0x3d372713, v184
	v_mul_f32_e32 v143, 0x3d372713, v182
	v_mul_f32_e32 v156, v183, v156
	v_mul_f32_e32 v157, v184, v157
	v_mul_f32_e32 v160, 0x3d372713, v185
	v_mul_f32_e32 v143, v182, v143
	v_fma_f32 v156, v183, v156, v183
	v_fma_f32 v157, v184, v157, v184
	v_mul_f32_e32 v160, v185, v160
	v_fma_f32 v143, v182, v143, v182
	v_mul_f32_e32 v156, 0x3fcc422a, v156
	v_mul_f32_e32 v157, 0x3fcc422a, v157
	v_fma_f32 v160, v185, v160, v185
	v_mul_f32_e32 v143, 0x3fcc422a, v143
	v_mul_f32_e32 v156, 0xbfb8aa3b, v156
	v_mul_f32_e32 v157, 0xbfb8aa3b, v157
	v_mul_f32_e32 v160, 0x3fcc422a, v160
	v_mul_f32_e32 v143, 0xbfb8aa3b, v143
	v_exp_f32_e32 v156, v156
	v_exp_f32_e32 v157, v157
	v_mul_f32_e32 v160, 0xbfb8aa3b, v160
	v_exp_f32_e32 v143, v143
	v_exp_f32_e32 v160, v160
	v_add_f32_e32 v156, 1.0, v156
	v_add_f32_e32 v157, 1.0, v157
	v_add_f32_e32 v143, 1.0, v143
	v_rcp_f32_e32 v156, v156
	v_rcp_f32_e32 v157, v157
	v_add_f32_e32 v160, 1.0, v160
	v_rcp_f32_e32 v143, v143
	v_rcp_f32_e32 v160, v160
	v_mul_f32_e32 v156, v183, v156
	v_mul_f32_e32 v157, v184, v157
	v_mul_f32_e32 v143, v182, v143
	v_mul_f32_e32 v160, v185, v160
	v_cvt_pk_bf16_f32 v156, v143, v156
	v_cvt_pk_bf16_f32 v157, v157, v160
	global_store_dwordx2 v[158:159], v[156:157], off offset:2048
	ds_read_b128 v[156:159], v180 offset:25344
	ds_read_b128 v[182:185], v180 offset:25408
	ds_read_b128 v[218:221], v180 offset:25472
	ds_read_b128 v[222:225], v180 offset:25536
	ds_read_b128 v[226:229], v180 offset:25600
	ds_read_b128 v[230:233], v180 offset:25664
	ds_read_b128 v[234:237], v180 offset:25728
	ds_read_b128 v[238:241], v180 offset:25792
	ds_read_b128 v[242:245], v179 offset:46848
	ds_read_b128 v[246:249], v179 offset:46912
	ds_read_b128 v[250:253], v179 offset:46976
	s_waitcnt lgkmcnt(10)
; DI unsigned cvt_pk_bf16(float lo, float hi) { unsigned r; asm volatile("v_cvt_pk_bf16_f32 %0, %1, %2" : "=v"(r) : "v"(lo), "v"(hi)); return r; }
; DI float sigm(float x) { return __builtin_amdgcn_rcpf(1.f + __expf(-x)); }
; #define MFMA16(a, b, c) __builtin_amdgcn_mfma_f32_16x16x32_bf16((a), (b), (c), 0, 0, 0)
; DI void ssm_mfma_phase(PP P, int l, unsigned char* lds, int G, int cid) {
;     ...
; #pragma unroll
;             for (int rt = 0; rt < 2; ++rt)
; #pragma unroll
;                 for (int jt = 0; jt < 4; ++jt) {
;                     f32x4 acc = {0.f, 0.f, 0.f, 0.f};
; #pragma unroll
;                     for (int ks = 0; ks < 8; ++ks) { const bf16x8 bf = *(const bf16x8*)(UL + (jt * 16 + n16) * 264 + ks * 32 + q4 * 8); acc = MFMA16(akc[rt][ks], bf, acc); }
; #pragma unroll
;                     for (int ks = 0; ks < 4; ++ks) { const bf16x8 bf = *(const bf16x8*)(SL + (jt * 16 + n16) * 136 + ks * 32 + q4 * 8); acc = MFMA16(akc[rt][8 + ks], bf, acc); }
;                     float o[4];
; #pragma unroll
;                     for (int k = 0; k < 4; ++k) { const float y = acc[k]; o[k] = y * sigm(1.5957691216f * (y + 0.044715f * y * y * y)); }
;                     u32x2 w; w.x = cvt_pk_bf16(o[0], o[1]); w.y = cvt_pk_bf16(o[2], o[3]);
;                     const int t = qt * 1024 + (jt * 16 + n16) * 16 + (wave * 2 + rt);
;                     *(u32x2*)(YG + ((size_t)b * SEQ + t) * 1024 + g * 16 + 4 * q4) = w;
;                 }
;         }
	v_mfma_f32_16x16x32_bf16 v[156:159], v[82:85], v[156:159], 0
	s_waitcnt lgkmcnt(9)
	v_mfma_f32_16x16x32_bf16 v[156:159], v[86:89], v[182:185], v[156:159]
	ds_read_b128 v[182:185], v179 offset:47040
	s_waitcnt lgkmcnt(9)
	v_mfma_f32_16x16x32_bf16 v[156:159], v[90:93], v[218:221], v[156:159]
	s_waitcnt lgkmcnt(8)
	v_mfma_f32_16x16x32_bf16 v[156:159], v[94:97], v[222:225], v[156:159]
	s_waitcnt lgkmcnt(7)
	v_mfma_f32_16x16x32_bf16 v[156:159], v[98:101], v[226:229], v[156:159]
	s_waitcnt lgkmcnt(6)
	v_mfma_f32_16x16x32_bf16 v[156:159], v[102:105], v[230:233], v[156:159]
	s_waitcnt lgkmcnt(5)
	v_mfma_f32_16x16x32_bf16 v[156:159], v[106:109], v[234:237], v[156:159]
	s_waitcnt lgkmcnt(4)
	v_mfma_f32_16x16x32_bf16 v[156:159], v[110:113], v[238:241], v[156:159]
	s_waitcnt lgkmcnt(3)
	v_mfma_f32_16x16x32_bf16 v[156:159], v[114:117], v[242:245], v[156:159]
	s_waitcnt lgkmcnt(2)
	v_mfma_f32_16x16x32_bf16 v[156:159], v[118:121], v[246:249], v[156:159]
	s_waitcnt lgkmcnt(1)
	v_mfma_f32_16x16x32_bf16 v[156:159], v[122:125], v[250:253], v[156:159]
	s_waitcnt lgkmcnt(0)
	v_mfma_f32_16x16x32_bf16 v[156:159], v[126:129], v[182:185], v[156:159]
	s_nop 7
	v_mul_f32_e32 v143, 0x3d372713, v156
	v_mul_f32_e32 v143, v156, v143
	v_fma_f32 v143, v156, v143, v156
	v_mul_f32_e32 v143, 0x3fcc422a, v143
	v_mul_f32_e32 v143, 0xbfb8aa3b, v143
	v_exp_f32_e32 v143, v143
	s_nop 0
	v_add_f32_e32 v143, 1.0, v143
	v_rcp_f32_e32 v143, v143
	s_nop 0
	v_mul_f32_e32 v143, v156, v143
	v_mul_f32_e32 v156, 0x3d372713, v157
	v_mul_f32_e32 v156, v157, v156
	v_fma_f32 v156, v157, v156, v157
	v_mul_f32_e32 v156, 0x3fcc422a, v156
	v_mul_f32_e32 v156, 0xbfb8aa3b, v156
	v_exp_f32_e32 v156, v156
	s_nop 0
	v_add_f32_e32 v156, 1.0, v156
	v_rcp_f32_e32 v156, v156
	s_nop 0
	v_mul_f32_e32 v156, v157, v156
	v_mul_f32_e32 v157, 0x3d372713, v158
	v_mul_f32_e32 v157, v158, v157
	v_fma_f32 v157, v158, v157, v158
	v_mul_f32_e32 v157, 0x3fcc422a, v157
	v_mul_f32_e32 v157, 0xbfb8aa3b, v157
	v_exp_f32_e32 v157, v157
	v_cvt_pk_bf16_f32 v156, v143, v156
	s_nop 0
	v_add_f32_e32 v157, 1.0, v157
	v_rcp_f32_e32 v157, v157
	s_nop 0
	v_mul_f32_e32 v157, v158, v157
	v_mul_f32_e32 v158, 0x3d372713, v159
	v_mul_f32_e32 v158, v159, v158
	v_fma_f32 v158, v159, v158, v159
	v_mul_f32_e32 v158, 0x3fcc422a, v158
	v_mul_f32_e32 v158, 0xbfb8aa3b, v158
	v_exp_f32_e32 v158, v158
	s_nop 0
	v_add_f32_e32 v158, 1.0, v158
	v_rcp_f32_e32 v158, v158
	s_nop 0
	v_mul_f32_e32 v158, v159, v158
	v_cvt_pk_bf16_f32 v157, v157, v158
	global_store_dwordx2 v[170:171], v[156:157], off offset:2048
	s_cbranch_scc1 .LBB0_234
; #define MFMA16(a, b, c) __builtin_amdgcn_mfma_f32_16x16x32_bf16((a), (b), (c), 0, 0, 0)
; DI void ssm_mfma_phase(PP P, int l, unsigned char* lds, int G, int cid) {
;     ...
;             __syncthreads();
; #pragma unroll
;             for (int k = 0; k < 2; ++k) { const int t = tid + 512 * k;
;                 const bf16_t* up = ZU + ((size_t)b * SEQ + qt * 1024 + t) * 1024 + g * 16;
;                 const u32x4 w0 = *(const u32x4*)up, w1 = *(const u32x4*)(up + 8);
;                 bf16_t* dp = UL + (t >> 4) * 264 + (t & 15) * 16; *(u32x4*)dp = w0; *(u32x4*)(dp + 8) = w1; }
;             __syncthreads();
; #pragma unroll
;             for (int jt = 0; jt < 4; ++jt) {
;                 f32x4 acc = {0.f, 0.f, 0.f, 0.f};
; #pragma unroll
;                 for (int ks = 0; ks < 8; ++ks) { const bf16x8 bf = *(const bf16x8*)(UL + (jt * 16 + n16) * 264 + ks * 32 + q4 * 8); acc = MFMA16(abp[ks], bf, acc); }
;                 *(f32x4*)(EL + (jt * 16 + n16) * 128 + wave * 16 + 4 * q4) = acc;
;             }
;             __syncthreads();
;             if (wave == 0) {
.LBB0_248:
	s_lshl_b32 s13, s12, 10
	s_add_u32 s4, s14, s13
	s_addc_u32 s5, s15, 0
	v_lshl_add_u64 v[156:157], s[4:5], 0, v[130:131]
	v_lshlrev_b64 v[156:157], 11, v[156:157]
	v_lshl_add_u64 v[160:161], s[16:17], 0, v[156:157]
	s_barrier
	global_load_dwordx4 v[156:159], v[160:161], off offset:16
	global_load_dwordx4 v[182:185], v[160:161], off
	v_lshl_add_u64 v[218:219], s[4:5], 0, v[138:139]
	v_lshlrev_b64 v[218:219], 11, v[218:219]
	v_lshl_add_u64 v[218:219], s[16:17], 0, v[218:219]
	global_load_dwordx4 v[222:225], v[218:219], off offset:16
	global_load_dwordx4 v[226:229], v[218:219], off
	s_and_b64 vcc, exec, s[40:41]
	s_waitcnt vmcnt(0)
	ds_write_b128 v177, v[182:185]
	ds_write_b128 v177, v[156:159] offset:16
	ds_write_b128 v178, v[226:229]
	ds_write_b128 v178, v[222:225] offset:16
	s_waitcnt lgkmcnt(0)
	s_barrier
	ds_read_b128 v[156:159], v180
	ds_read_b128 v[182:185], v180 offset:64
	ds_read_b128 v[218:221], v180 offset:128
	ds_read_b128 v[222:225], v180 offset:192
	ds_read_b128 v[226:229], v180 offset:256
	ds_read_b128 v[230:233], v180 offset:320
	ds_read_b128 v[234:237], v180 offset:384
	ds_read_b128 v[238:241], v180 offset:448
	s_waitcnt lgkmcnt(7)
	v_mfma_f32_16x16x32_bf16 v[156:159], v[2:5], v[156:159], 0
	s_waitcnt lgkmcnt(6)
	v_mfma_f32_16x16x32_bf16 v[156:159], v[6:9], v[182:185], v[156:159]
	s_waitcnt lgkmcnt(5)
	v_mfma_f32_16x16x32_bf16 v[156:159], v[10:13], v[218:221], v[156:159]
	s_waitcnt lgkmcnt(4)
	v_mfma_f32_16x16x32_bf16 v[156:159], v[14:17], v[222:225], v[156:159]
	s_waitcnt lgkmcnt(3)
	v_mfma_f32_16x16x32_bf16 v[156:159], v[18:21], v[226:229], v[156:159]
	s_waitcnt lgkmcnt(2)
	v_mfma_f32_16x16x32_bf16 v[156:159], v[22:25], v[230:233], v[156:159]
	s_waitcnt lgkmcnt(1)
	v_mfma_f32_16x16x32_bf16 v[156:159], v[26:29], v[234:237], v[156:159]
	s_waitcnt lgkmcnt(0)
	v_mfma_f32_16x16x32_bf16 v[156:159], v[30:33], v[238:241], v[156:159]
	s_nop 7
	ds_write_b128 v172, v[156:159] offset:51200
	ds_read_b128 v[156:159], v180 offset:8448
	ds_read_b128 v[182:185], v180 offset:8512
	ds_read_b128 v[218:221], v180 offset:8576
	ds_read_b128 v[222:225], v180 offset:8640
	ds_read_b128 v[226:229], v180 offset:8704
	ds_read_b128 v[230:233], v180 offset:8768
	ds_read_b128 v[234:237], v180 offset:8832
	ds_read_b128 v[238:241], v180 offset:8896
	s_waitcnt lgkmcnt(7)
	v_mfma_f32_16x16x32_bf16 v[156:159], v[2:5], v[156:159], 0
	s_waitcnt lgkmcnt(6)
	v_mfma_f32_16x16x32_bf16 v[156:159], v[6:9], v[182:185], v[156:159]
	s_waitcnt lgkmcnt(5)
	v_mfma_f32_16x16x32_bf16 v[156:159], v[10:13], v[218:221], v[156:159]
	s_waitcnt lgkmcnt(4)
	v_mfma_f32_16x16x32_bf16 v[156:159], v[14:17], v[222:225], v[156:159]
	s_waitcnt lgkmcnt(3)
	v_mfma_f32_16x16x32_bf16 v[156:159], v[18:21], v[226:229], v[156:159]
	s_waitcnt lgkmcnt(2)
	v_mfma_f32_16x16x32_bf16 v[156:159], v[22:25], v[230:233], v[156:159]
	s_waitcnt lgkmcnt(1)
	v_mfma_f32_16x16x32_bf16 v[156:159], v[26:29], v[234:237], v[156:159]
	s_waitcnt lgkmcnt(0)
	v_mfma_f32_16x16x32_bf16 v[156:159], v[30:33], v[238:241], v[156:159]
	s_nop 7
	ds_write_b128 v172, v[156:159] offset:59392
	ds_read_b128 v[156:159], v180 offset:16896
	ds_read_b128 v[182:185], v180 offset:16960
	ds_read_b128 v[218:221], v180 offset:17024
	ds_read_b128 v[222:225], v180 offset:17088
	ds_read_b128 v[226:229], v180 offset:17152
	ds_read_b128 v[230:233], v180 offset:17216
	ds_read_b128 v[234:237], v180 offset:17280
	ds_read_b128 v[238:241], v180 offset:17344
	s_waitcnt lgkmcnt(7)
	v_mfma_f32_16x16x32_bf16 v[156:159], v[2:5], v[156:159], 0
	s_waitcnt lgkmcnt(6)
	v_mfma_f32_16x16x32_bf16 v[156:159], v[6:9], v[182:185], v[156:159]
	s_waitcnt lgkmcnt(5)
	v_mfma_f32_16x16x32_bf16 v[156:159], v[10:13], v[218:221], v[156:159]
	s_waitcnt lgkmcnt(4)
	v_mfma_f32_16x16x32_bf16 v[156:159], v[14:17], v[222:225], v[156:159]
	s_waitcnt lgkmcnt(3)
	v_mfma_f32_16x16x32_bf16 v[156:159], v[18:21], v[226:229], v[156:159]
	s_waitcnt lgkmcnt(2)
	v_mfma_f32_16x16x32_bf16 v[156:159], v[22:25], v[230:233], v[156:159]
	s_waitcnt lgkmcnt(1)
	v_mfma_f32_16x16x32_bf16 v[156:159], v[26:29], v[234:237], v[156:159]
	s_waitcnt lgkmcnt(0)
	v_mfma_f32_16x16x32_bf16 v[156:159], v[30:33], v[238:241], v[156:159]
	s_nop 7
	ds_write_b128 v173, v[156:159] offset:16384
	ds_read_b128 v[156:159], v180 offset:25344
	ds_read_b128 v[182:185], v180 offset:25408
	ds_read_b128 v[218:221], v180 offset:25472
	ds_read_b128 v[222:225], v180 offset:25536
	ds_read_b128 v[226:229], v180 offset:25600
	ds_read_b128 v[230:233], v180 offset:25664
	ds_read_b128 v[234:237], v180 offset:25728
	ds_read_b128 v[238:241], v180 offset:25792
	s_waitcnt lgkmcnt(7)
	v_mfma_f32_16x16x32_bf16 v[156:159], v[2:5], v[156:159], 0
	s_waitcnt lgkmcnt(6)
	v_mfma_f32_16x16x32_bf16 v[156:159], v[6:9], v[182:185], v[156:159]
	s_waitcnt lgkmcnt(5)
	v_mfma_f32_16x16x32_bf16 v[156:159], v[10:13], v[218:221], v[156:159]
	s_waitcnt lgkmcnt(4)
	v_mfma_f32_16x16x32_bf16 v[156:159], v[14:17], v[222:225], v[156:159]
	s_waitcnt lgkmcnt(3)
	v_mfma_f32_16x16x32_bf16 v[156:159], v[18:21], v[226:229], v[156:159]
	s_waitcnt lgkmcnt(2)
	v_mfma_f32_16x16x32_bf16 v[156:159], v[22:25], v[230:233], v[156:159]
	s_waitcnt lgkmcnt(1)
	v_mfma_f32_16x16x32_bf16 v[156:159], v[26:29], v[234:237], v[156:159]
	s_waitcnt lgkmcnt(0)
	v_mfma_f32_16x16x32_bf16 v[156:159], v[30:33], v[238:241], v[156:159]
	s_nop 7
	ds_write_b128 v173, v[156:159] offset:24576
	s_waitcnt lgkmcnt(0)
	s_barrier
	s_cbranch_vccnz .LBB0_247
	s_mov_b32 s42, -16
	v_mov_b32_e32 v143, v176
	v_mov_b32_e32 v156, v175
